# adds diff-attention Q*K^T block: K fragment LDS reads hoisted into separate registers, s_nop 5/6 and lgkmcnt(0) stalls removed
# speedup vs baseline: 1.0458x; 1.0004x over previous
;   DI void tile(const u16* Ks, const u16* Vts) {
;     ...
;     for (int qb = 0; qb < NQB; ++qb) base[qb] = (m[qb] == -INFINITY) ? 0.f : m[qb];
;     f32x4 s[4][NQB];
;     __builtin_amdgcn_s_setprio(1);
; #pragma unroll
;     for (int kb = 0; kb < 4; ++kb) {
; #pragma unroll
;       for (int qb = 0; qb < NQB; ++qb) s[kb][qb] = f32x4{-base[qb], -base[qb], -base[qb], -base[qb]};
; #pragma unroll
;       for (int ks = 0; ks < DK / 32; ++ks) {
;         bf16x8 kf = *reinterpret_cast<const bf16x8*>(Ks + (kb * 16 + fr) * KSTR + ks * 32 + fq * 8);
; #pragma unroll
;         for (int qb = 0; qb < NQB; ++qb) s[kb][qb] = __builtin_amdgcn_mfma_f32_16x16x32_bf16(kf, qf[qb][ks], s[kb][qb], 0, 0, 0);
;       }
;     }
;     __builtin_amdgcn_s_setprio(0);
;     bf16x8 pf[NQB][2];
; #pragma unroll
;     for (int qb = 0; qb < NQB; ++qb) {
;       float mx = -INFINITY;
; #pragma unroll
;       for (int kb = 0; kb < 4; ++kb) {
; #pragma unroll
;         for (int j = 0; j < 4; ++j) mx = fmaxf(mx, s[kb][qb][j]); }
;       mx = fmaxf(mx, __shfl_xor(mx, 16));
;       mx = fmaxf(mx, __shfl_xor(mx, 32));
;       const float mn = fmaxf(m[qb], base[qb] + mx);
;       const bool changed = __any(mn > m[qb]);
;       float sum = 0.f;
;       if (changed) {
;         const float delta = mn - base[qb];
;         const float alpha = __builtin_amdgcn_exp2f(m[qb] - mn);
; #pragma unroll
;         for (int kb = 0; kb < 4; ++kb) {
; #pragma unroll
;           for (int j = 0; j < 4; ++j) { float e = __builtin_amdgcn_exp2f(s[kb][qb][j] - delta); s[kb][qb][j] = e; sum += e; } }
;         l[qb] = l[qb] * alpha + sum;
; #pragma unroll
;         for (int d = 0; d < DV / 16; ++d) { o[qb][d][0] *= alpha; o[qb][d][1] *= alpha; o[qb][d][2] *= alpha; o[qb][d][3] *= alpha; }
.LBB0_198:
	v_cmp_le_u32_e32 vcc, s6, v193
	s_and_saveexec_b64 s[6:7], vcc
	s_cbranch_execz .LBB0_206
	v_cmp_neq_f32_e32 vcc, s42, v115
	v_mov_b32_e32 v98, v234
	s_nop 0
	v_cndmask_b32_e32 v114, 0, v115, vcc
	v_cmp_neq_f32_e32 vcc, s42, v202
	v_and_b32_e32 v99, 15, v98
	s_nop 0
	v_cndmask_b32_e32 v205, 0, v202, vcc
	s_setprio 1
	v_lshrrev_b32_e32 v98, 1, v98
	v_and_b32_e32 v198, 24, v98
	v_lshlrev_b32_e32 v98, 1, v198
	v_mul_u32_u24_e32 v200, 0x90, v99
	v_add3_u32 v128, v196, v98, v200
	ds_read_b128 v[208:211], v128
	ds_read_b128 v[212:215], v128 offset:64
	ds_read_b128 v[216:219], v128 offset:2304
	ds_read_b128 v[220:223], v128 offset:2368
	ds_read_b128 v[224:227], v128 offset:4608
	ds_read_b128 v[124:127], v128 offset:4672
	v_xor_b32_e32 v110, 0x80000000, v114
	v_mov_b32_e32 v111, v110
	v_mov_b32_e32 v112, v110
	v_mov_b32_e32 v113, v110
	v_xor_b32_e32 v116, 0x80000000, v205
	v_mov_b32_e32 v117, v116
	v_mov_b32_e32 v118, v116
	v_mov_b32_e32 v119, v116
	s_waitcnt lgkmcnt(5)
	v_mfma_f32_16x16x32_bf16 v[102:105], v[208:211], v[34:37], v[110:113]
	s_waitcnt lgkmcnt(4)
	v_mfma_f32_16x16x32_bf16 v[162:165], v[212:215], v[38:41], v[102:105]
	v_mfma_f32_16x16x32_bf16 v[98:101], v[208:211], v[42:45], v[116:119]
	v_mfma_f32_16x16x32_bf16 v[98:101], v[212:215], v[46:49], v[98:101]
	ds_read_b128 v[208:211], v128 offset:6912
	ds_read_b128 v[212:215], v128 offset:6976
	s_waitcnt lgkmcnt(5)
	v_mfma_f32_16x16x32_bf16 v[106:109], v[216:219], v[34:37], v[110:113]
	s_waitcnt lgkmcnt(4)
	v_mfma_f32_16x16x32_bf16 v[166:169], v[220:223], v[38:41], v[106:109]
	v_mfma_f32_16x16x32_bf16 v[102:105], v[216:219], v[42:45], v[116:119]
	v_mfma_f32_16x16x32_bf16 v[102:105], v[220:223], v[46:49], v[102:105]
	s_waitcnt lgkmcnt(3)
	v_mfma_f32_16x16x32_bf16 v[120:123], v[224:227], v[34:37], v[110:113]
	s_waitcnt lgkmcnt(2)
	v_mfma_f32_16x16x32_bf16 v[170:173], v[124:127], v[38:41], v[120:123]
	v_mfma_f32_16x16x32_bf16 v[106:109], v[224:227], v[42:45], v[116:119]
	s_waitcnt lgkmcnt(1)
	v_mfma_f32_16x16x32_bf16 v[110:113], v[208:211], v[34:37], v[110:113]
	v_mfma_f32_16x16x32_bf16 v[116:119], v[208:211], v[42:45], v[116:119]
	v_mfma_f32_16x16x32_bf16 v[106:109], v[124:127], v[46:49], v[106:109]
	s_waitcnt lgkmcnt(0)
	v_mfma_f32_16x16x32_bf16 v[174:177], v[212:215], v[38:41], v[110:113]
	v_mfma_f32_16x16x32_bf16 v[110:113], v[212:215], v[46:49], v[116:119]
	s_setprio 0
	s_nop 1
	v_and_b32_e32 v117, 64, v239
	v_xor_b32_e32 v116, 16, v239
	v_add_u32_e32 v117, 64, v117
	v_cmp_lt_i32_e32 vcc, v116, v117
	v_xor_b32_e32 v119, 32, v239
	s_nop 0
	v_cndmask_b32_e32 v116, v239, v116, vcc
	v_lshlrev_b32_e32 v204, 2, v116
	v_max3_f32 v116, v162, s42, v163
	v_max3_f32 v116, v116, v164, v165
	v_max3_f32 v116, v116, v166, v167
	v_max3_f32 v116, v116, v168, v169
	v_max3_f32 v116, v116, v170, v171
	v_max3_f32 v116, v116, v172, v173
	v_max3_f32 v116, v116, v174, v175
	v_max3_f32 v116, v116, v176, v177
	ds_bpermute_b32 v118, v204, v116
	v_cmp_lt_i32_e32 vcc, v119, v117
	s_nop 1
	v_cndmask_b32_e32 v117, v239, v119, vcc
	v_lshlrev_b32_e32 v206, 2, v117
	s_waitcnt lgkmcnt(0)
	v_max_f32_e32 v117, v118, v118
	v_max_f32_e32 v116, v116, v117
	ds_bpermute_b32 v117, v206, v116
	s_waitcnt lgkmcnt(0)
	v_max_f32_e32 v117, v117, v117
	v_max_f32_e32 v116, v116, v117
	v_add_f32_e32 v116, v114, v116
	v_max_f32_e32 v117, v115, v115
	v_max_f32_e32 v199, v117, v116
	v_cmp_gt_f32_e32 vcc, v199, v115
	s_cbranch_vccz .LBB0_208
	v_sub_f32_e32 v129, v199, v114
	v_sub_f32_e32 v114, v162, v129
	v_exp_f32_e32 v114, v114
	v_sub_f32_e32 v130, v115, v199
	v_sub_f32_e32 v115, v163, v129
	v_exp_f32_e32 v115, v115
	v_sub_f32_e32 v116, v164, v129
	v_exp_f32_e32 v116, v116
	v_sub_f32_e32 v117, v165, v129
	v_exp_f32_e32 v117, v117
	v_sub_f32_e32 v118, v166, v129
	v_add_f32_e32 v119, 0, v114
	v_exp_f32_e32 v118, v118
	v_add_f32_e32 v119, v115, v119
	v_add_f32_e32 v119, v116, v119
	v_add_f32_e32 v119, v117, v119
	v_add_f32_e32 v123, v118, v119
	v_sub_f32_e32 v119, v167, v129
	v_exp_f32_e32 v119, v119
	v_sub_f32_e32 v120, v168, v129
	v_exp_f32_e32 v120, v120
	v_sub_f32_e32 v121, v169, v129
	v_exp_f32_e32 v121, v121
	v_sub_f32_e32 v122, v170, v129
	v_exp_f32_e32 v122, v122
	v_add_f32_e32 v123, v119, v123
	v_add_f32_e32 v123, v120, v123
	v_add_f32_e32 v123, v121, v123
	v_add_f32_e32 v127, v122, v123
	v_sub_f32_e32 v123, v171, v129
	v_exp_f32_e32 v123, v123
	v_sub_f32_e32 v124, v172, v129
	v_exp_f32_e32 v124, v124
	v_sub_f32_e32 v125, v173, v129
	v_exp_f32_e32 v125, v125
	v_sub_f32_e32 v126, v174, v129
	v_exp_f32_e32 v126, v126
	v_add_f32_e32 v127, v123, v127
	v_add_f32_e32 v127, v124, v127
	v_add_f32_e32 v127, v125, v127
	v_add_f32_e32 v131, v126, v127
	v_sub_f32_e32 v127, v175, v129
	v_exp_f32_e32 v127, v127
	v_sub_f32_e32 v128, v176, v129
	v_exp_f32_e32 v128, v128
	v_sub_f32_e32 v129, v177, v129
	v_exp_f32_e32 v129, v129
	v_exp_f32_e32 v130, v130
	v_add_f32_e32 v131, v127, v131
	v_add_f32_e32 v131, v128, v131
	v_add_f32_e32 v203, v129, v131
	v_fmac_f32_e32 v203, v201, v130
	v_pk_mul_f32 v[160:161], v[68:69], v[130:131] op_sel_hi:[1,0]
	v_pk_mul_f32 v[158:159], v[66:67], v[130:131] op_sel_hi:[1,0]
	v_pk_mul_f32 v[156:157], v[72:73], v[130:131] op_sel_hi:[1,0]
	v_pk_mul_f32 v[154:155], v[70:71], v[130:131] op_sel_hi:[1,0]
	v_pk_mul_f32 v[152:153], v[76:77], v[130:131] op_sel_hi:[1,0]
	v_pk_mul_f32 v[150:151], v[74:75], v[130:131] op_sel_hi:[1,0]
	v_pk_mul_f32 v[148:149], v[80:81], v[130:131] op_sel_hi:[1,0]
	v_pk_mul_f32 v[146:147], v[78:79], v[130:131] op_sel_hi:[1,0]
	v_pk_mul_f32 v[144:145], v[84:85], v[130:131] op_sel_hi:[1,0]
	v_pk_mul_f32 v[142:143], v[82:83], v[130:131] op_sel_hi:[1,0]
	v_pk_mul_f32 v[140:141], v[92:93], v[130:131] op_sel_hi:[1,0]
	v_pk_mul_f32 v[138:139], v[90:91], v[130:131] op_sel_hi:[1,0]
	v_pk_mul_f32 v[136:137], v[88:89], v[130:131] op_sel_hi:[1,0]
	v_pk_mul_f32 v[134:135], v[86:87], v[130:131] op_sel_hi:[1,0]
	v_pk_mul_f32 v[132:133], v[96:97], v[130:131] op_sel_hi:[1,0]
	v_pk_mul_f32 v[130:131], v[94:95], v[130:131] op_sel_hi:[1,0]
	s_cbranch_execnz .LBB0_202
